# v45 + guard: 0.85us s_sleep for all waves after the in-proj grid barrier (co-resident WG release skew made early P loads unsafe in de-phased stress runs)
# speedup vs baseline: 1.0384x; 1.0004x over previous
.LBB0_326:
	s_or_b64 exec, exec, s[0:1]
	s_lshl_b32 s22, s84, 6
	s_mov_b64 s[0:1], -1
	s_and_b64 vcc, exec, s[8:9]
	s_waitcnt lgkmcnt(0)
	s_barrier
	s_sleep 32
	s_cbranch_vccz .LBB0_500
	v_readlane_b32 s0, v254, 29
	v_readlane_b32 s1, v254, 30
	s_and_b64 vcc, exec, s[0:1]
	s_cbranch_vccz .LBB0_329
	s_sleep 0x7f
